# non-temporal (nt) output stores in the SwiGLU and in-proj GEMM epilogues (streamed act/proj tiles), on top of v56
# speedup vs baseline: 1.0203x; 1.0081x over previous
.LBB0_147:
	s_add_u32 s18, s16, 0xfffc0080
	s_addc_u32 s19, s17, -1
	s_add_i32 s83, 0, 0x10000
	v_add_u32_e32 v140, s83, v143
	ds_read_b128 v[146:149], v140
	ds_read_b128 v[150:153], v140 offset:1024
	ds_read_b128 v[154:157], v140 offset:2048
	ds_read_b128 v[158:161], v140 offset:3072
	s_cmp_eq_u32 s82, 12
	s_cselect_b32 s23, s12, s19
	s_cselect_b32 s22, s29, s18
	s_cselect_b32 s19, s9, s79
	s_cselect_b32 s18, s34, s61
	v_lshl_add_u64 v[140:141], s[16:17], 0, v[138:139]
	s_add_i32 m0, s15, 0xc000
	ds_read_b128 v[162:165], v145
	ds_read_b128 v[166:169], v145 offset:1024
	ds_read_b128 v[170:173], v145 offset:2048
	ds_read_b128 v[174:177], v145 offset:3072
	ds_read_b128 v[178:181], v145 offset:4096
	ds_read_b128 v[182:185], v145 offset:5120
	ds_read_b128 v[186:189], v145 offset:6144
	ds_read_b128 v[190:193], v145 offset:7168
	global_load_lds_dwordx4 v[140:141], off
	v_lshl_add_u64 v[140:141], s[16:17], 0, v[136:137]
	s_add_i32 m0, s15, 0xe000
	s_nop 0
	global_load_lds_dwordx4 v[140:141], off
	s_waitcnt lgkmcnt(8)
	s_waitcnt vmcnt(10)
	s_barrier
	s_waitcnt lgkmcnt(0)
	s_waitcnt lgkmcnt(0)
	v_mfma_f32_16x16x32_bf16 v[126:129], v[146:149], v[162:165], v[126:129]
	v_mfma_f32_16x16x32_bf16 v[118:121], v[154:157], v[162:165], v[118:121]
	v_mfma_f32_16x16x32_bf16 v[110:113], v[146:149], v[170:173], v[110:113]
	v_mfma_f32_16x16x32_bf16 v[102:105], v[154:157], v[170:173], v[102:105]
	v_mfma_f32_16x16x32_bf16 v[94:97], v[146:149], v[178:181], v[94:97]
	v_mfma_f32_16x16x32_bf16 v[86:89], v[154:157], v[178:181], v[86:89]
	v_mfma_f32_16x16x32_bf16 v[78:81], v[146:149], v[186:189], v[78:81]
	v_mfma_f32_16x16x32_bf16 v[70:73], v[154:157], v[186:189], v[70:73]
	v_mfma_f32_16x16x32_bf16 v[126:129], v[150:153], v[166:169], v[126:129]
	v_mfma_f32_16x16x32_bf16 v[118:121], v[158:161], v[166:169], v[118:121]
	v_mfma_f32_16x16x32_bf16 v[110:113], v[150:153], v[174:177], v[110:113]
	v_mfma_f32_16x16x32_bf16 v[102:105], v[158:161], v[174:177], v[102:105]
	v_mfma_f32_16x16x32_bf16 v[94:97], v[150:153], v[182:185], v[94:97]
	v_mfma_f32_16x16x32_bf16 v[86:89], v[158:161], v[182:185], v[86:89]
	v_mfma_f32_16x16x32_bf16 v[78:81], v[150:153], v[190:193], v[78:81]
	v_mfma_f32_16x16x32_bf16 v[70:73], v[158:161], v[190:193], v[70:73]
	s_barrier
	s_add_i32 s86, 0, 0x14000
	v_add_u32_e32 v140, s86, v143
	s_add_i32 s83, s83, s51
	ds_read_b128 v[194:197], v140
	ds_read_b128 v[208:211], v140 offset:1024
	ds_read_b128 v[212:215], v140 offset:2048
	ds_read_b128 v[216:219], v140 offset:3072
	v_lshl_add_u64 v[140:141], s[18:19], 0, v[16:17]
	s_mov_b32 m0, s83
	v_lshl_add_u64 v[220:221], s[18:19], 0, v[130:131]
	global_load_lds_dwordx4 v[140:141], off
	s_add_i32 m0, s83, 0x2000
	s_nop 0
	global_load_lds_dwordx4 v[220:221], off
	s_waitcnt vmcnt(10)
	s_barrier
	s_waitcnt lgkmcnt(0)
	s_waitcnt lgkmcnt(0)
	v_mfma_f32_16x16x32_bf16 v[122:125], v[194:197], v[162:165], v[122:125]
	v_mfma_f32_16x16x32_bf16 v[114:117], v[212:215], v[162:165], v[114:117]
	v_mfma_f32_16x16x32_bf16 v[106:109], v[194:197], v[170:173], v[106:109]
	v_mfma_f32_16x16x32_bf16 v[98:101], v[212:215], v[170:173], v[98:101]
	v_mfma_f32_16x16x32_bf16 v[90:93], v[194:197], v[178:181], v[90:93]
	v_mfma_f32_16x16x32_bf16 v[82:85], v[212:215], v[178:181], v[82:85]
	v_mfma_f32_16x16x32_bf16 v[74:77], v[194:197], v[186:189], v[74:77]
	v_mfma_f32_16x16x32_bf16 v[66:69], v[212:215], v[186:189], v[66:69]
	v_mfma_f32_16x16x32_bf16 v[122:125], v[208:211], v[166:169], v[122:125]
	v_mfma_f32_16x16x32_bf16 v[114:117], v[216:219], v[166:169], v[114:117]
	v_mfma_f32_16x16x32_bf16 v[106:109], v[208:211], v[174:177], v[106:109]
	v_mfma_f32_16x16x32_bf16 v[98:101], v[216:219], v[174:177], v[98:101]
	v_mfma_f32_16x16x32_bf16 v[90:93], v[208:211], v[182:185], v[90:93]
	v_mfma_f32_16x16x32_bf16 v[82:85], v[216:219], v[182:185], v[82:85]
	v_mfma_f32_16x16x32_bf16 v[74:77], v[208:211], v[190:193], v[74:77]
	v_mfma_f32_16x16x32_bf16 v[66:69], v[216:219], v[190:193], v[66:69]
	s_mov_b32 m0, s15
	v_lshl_add_u64 v[222:223], s[22:23], 0, v[134:135]
	s_barrier
	ds_read_b128 v[162:165], v145 offset:16384
	ds_read_b128 v[166:169], v145 offset:17408
	ds_read_b128 v[170:173], v145 offset:18432
	ds_read_b128 v[174:177], v145 offset:19456
	ds_read_b128 v[178:181], v145 offset:20480
	ds_read_b128 v[182:185], v145 offset:21504
	ds_read_b128 v[186:189], v145 offset:22528
	ds_read_b128 v[190:193], v145 offset:23552
	global_load_lds_dwordx4 v[222:223], off
	v_lshl_add_u64 v[224:225], s[22:23], 0, v[132:133]
	s_mov_b32 m0, s54
	s_nop 0
	global_load_lds_dwordx4 v[224:225], off
	s_barrier
	s_waitcnt lgkmcnt(0)
	s_waitcnt lgkmcnt(0)
	v_mfma_f32_16x16x32_bf16 v[62:65], v[146:149], v[162:165], v[62:65]
	v_mfma_f32_16x16x32_bf16 v[54:57], v[154:157], v[162:165], v[54:57]
	v_mfma_f32_16x16x32_bf16 v[46:49], v[146:149], v[170:173], v[46:49]
	v_mfma_f32_16x16x32_bf16 v[38:41], v[154:157], v[170:173], v[38:41]
	v_mfma_f32_16x16x32_bf16 v[30:33], v[146:149], v[178:181], v[30:33]
	v_mfma_f32_16x16x32_bf16 v[22:25], v[154:157], v[178:181], v[22:25]
	v_mfma_f32_16x16x32_bf16 v[12:15], v[146:149], v[186:189], v[12:15]
	v_mfma_f32_16x16x32_bf16 v[4:7], v[154:157], v[186:189], v[4:7]
	v_mfma_f32_16x16x32_bf16 v[62:65], v[150:153], v[166:169], v[62:65]
	v_mfma_f32_16x16x32_bf16 v[54:57], v[158:161], v[166:169], v[54:57]
	v_mfma_f32_16x16x32_bf16 v[46:49], v[150:153], v[174:177], v[46:49]
	v_mfma_f32_16x16x32_bf16 v[38:41], v[158:161], v[174:177], v[38:41]
	v_mfma_f32_16x16x32_bf16 v[30:33], v[150:153], v[182:185], v[30:33]
	v_mfma_f32_16x16x32_bf16 v[22:25], v[158:161], v[182:185], v[22:25]
	v_mfma_f32_16x16x32_bf16 v[12:15], v[150:153], v[190:193], v[12:15]
	v_mfma_f32_16x16x32_bf16 v[4:7], v[158:161], v[190:193], v[4:7]
	s_barrier
	s_add_u32 s84, s18, 0x40000
	s_addc_u32 s85, s19, 0
	s_add_i32 s83, s86, s51
	v_lshl_add_u64 v[146:147], s[84:85], 0, v[16:17]
	s_mov_b32 m0, s83
	s_nop 0
	global_load_lds_dwordx4 v[146:147], off
	v_lshl_add_u64 v[146:147], s[84:85], 0, v[130:131]
	s_add_i32 m0, s83, 0x2000
	s_nop 0
	global_load_lds_dwordx4 v[146:147], off
	s_waitcnt vmcnt(10)
	s_barrier
	v_mfma_f32_16x16x32_bf16 v[58:61], v[194:197], v[162:165], v[58:61]
	v_mfma_f32_16x16x32_bf16 v[50:53], v[212:215], v[162:165], v[50:53]
	v_mfma_f32_16x16x32_bf16 v[42:45], v[194:197], v[170:173], v[42:45]
	v_mfma_f32_16x16x32_bf16 v[34:37], v[212:215], v[170:173], v[34:37]
	v_mfma_f32_16x16x32_bf16 v[26:29], v[194:197], v[178:181], v[26:29]
	v_mfma_f32_16x16x32_bf16 v[18:21], v[212:215], v[178:181], v[18:21]
	v_mfma_f32_16x16x32_bf16 v[8:11], v[194:197], v[186:189], v[8:11]
	v_mfma_f32_16x16x32_bf16 v[0:3], v[212:215], v[186:189], v[0:3]
	v_mfma_f32_16x16x32_bf16 v[58:61], v[208:211], v[166:169], v[58:61]
	v_mfma_f32_16x16x32_bf16 v[50:53], v[216:219], v[166:169], v[50:53]
	v_mfma_f32_16x16x32_bf16 v[42:45], v[208:211], v[174:177], v[42:45]
	v_mfma_f32_16x16x32_bf16 v[34:37], v[216:219], v[174:177], v[34:37]
	v_mfma_f32_16x16x32_bf16 v[26:29], v[208:211], v[182:185], v[26:29]
	v_mfma_f32_16x16x32_bf16 v[18:21], v[216:219], v[182:185], v[18:21]
	v_mfma_f32_16x16x32_bf16 v[8:11], v[208:211], v[190:193], v[8:11]
	v_mfma_f32_16x16x32_bf16 v[0:3], v[216:219], v[190:193], v[0:3]
	s_add_i32 s83, 0, 0x18000
	v_add_u32_e32 v158, s83, v143
	s_barrier
	ds_read_b128 v[146:149], v158
	ds_read_b128 v[150:153], v158 offset:1024
	ds_read_b128 v[154:157], v158 offset:2048
	ds_read_b128 v[158:161], v158 offset:3072
	s_add_u32 s22, s22, 0x40000
	s_addc_u32 s23, s23, 0
	s_mov_b32 m0, s55
	v_lshl_add_u64 v[194:195], s[22:23], 0, v[134:135]
	ds_read_b128 v[162:165], v145 offset:32768
	ds_read_b128 v[166:169], v145 offset:33792
	ds_read_b128 v[170:173], v145 offset:34816
	ds_read_b128 v[174:177], v145 offset:35840
	ds_read_b128 v[178:181], v145 offset:36864
	ds_read_b128 v[182:185], v145 offset:37888
	ds_read_b128 v[186:189], v145 offset:38912
	ds_read_b128 v[190:193], v145 offset:39936
	global_load_lds_dwordx4 v[194:195], off
	v_lshl_add_u64 v[194:195], s[22:23], 0, v[132:133]
	s_mov_b32 m0, s56
	s_nop 0
	global_load_lds_dwordx4 v[194:195], off
	s_waitcnt lgkmcnt(8)
	s_waitcnt vmcnt(10)
	s_barrier
	s_waitcnt lgkmcnt(0)
	s_waitcnt lgkmcnt(0)
	v_mfma_f32_16x16x32_bf16 v[126:129], v[146:149], v[162:165], v[126:129]
	v_mfma_f32_16x16x32_bf16 v[118:121], v[154:157], v[162:165], v[118:121]
	v_mfma_f32_16x16x32_bf16 v[110:113], v[146:149], v[170:173], v[110:113]
	v_mfma_f32_16x16x32_bf16 v[102:105], v[154:157], v[170:173], v[102:105]
	v_mfma_f32_16x16x32_bf16 v[94:97], v[146:149], v[178:181], v[94:97]
	v_mfma_f32_16x16x32_bf16 v[86:89], v[154:157], v[178:181], v[86:89]
	v_mfma_f32_16x16x32_bf16 v[78:81], v[146:149], v[186:189], v[78:81]
	v_mfma_f32_16x16x32_bf16 v[70:73], v[154:157], v[186:189], v[70:73]
	v_mfma_f32_16x16x32_bf16 v[126:129], v[150:153], v[166:169], v[126:129]
	v_mfma_f32_16x16x32_bf16 v[118:121], v[158:161], v[166:169], v[118:121]
	v_mfma_f32_16x16x32_bf16 v[110:113], v[150:153], v[174:177], v[110:113]
	v_mfma_f32_16x16x32_bf16 v[102:105], v[158:161], v[174:177], v[102:105]
	v_mfma_f32_16x16x32_bf16 v[94:97], v[150:153], v[182:185], v[94:97]
	v_mfma_f32_16x16x32_bf16 v[86:89], v[158:161], v[182:185], v[86:89]
	v_mfma_f32_16x16x32_bf16 v[78:81], v[150:153], v[190:193], v[78:81]
	v_mfma_f32_16x16x32_bf16 v[70:73], v[158:161], v[190:193], v[70:73]
	s_barrier
	s_add_i32 s22, 0, 0x1c000
	s_add_i32 s23, s83, s51
	v_add_u32_e32 v216, s22, v143
	v_lshl_add_u64 v[140:141], v[140:141], 0, s[10:11]
	s_mov_b32 m0, s23
	ds_read_b128 v[194:197], v216
	ds_read_b128 v[208:211], v216 offset:1024
	ds_read_b128 v[212:215], v216 offset:2048
	ds_read_b128 v[216:219], v216 offset:3072
	global_load_lds_dwordx4 v[140:141], off
	v_lshl_add_u64 v[140:141], v[220:221], 0, s[10:11]
	s_add_i32 m0, s23, 0x2000
	s_nop 0
	global_load_lds_dwordx4 v[140:141], off
	s_waitcnt vmcnt(10)
	s_barrier
	s_waitcnt lgkmcnt(0)
	s_waitcnt lgkmcnt(0)
	v_mfma_f32_16x16x32_bf16 v[122:125], v[194:197], v[162:165], v[122:125]
	v_mfma_f32_16x16x32_bf16 v[114:117], v[212:215], v[162:165], v[114:117]
	v_mfma_f32_16x16x32_bf16 v[106:109], v[194:197], v[170:173], v[106:109]
	v_mfma_f32_16x16x32_bf16 v[98:101], v[212:215], v[170:173], v[98:101]
	v_mfma_f32_16x16x32_bf16 v[90:93], v[194:197], v[178:181], v[90:93]
	v_mfma_f32_16x16x32_bf16 v[82:85], v[212:215], v[178:181], v[82:85]
	v_mfma_f32_16x16x32_bf16 v[74:77], v[194:197], v[186:189], v[74:77]
	v_mfma_f32_16x16x32_bf16 v[66:69], v[212:215], v[186:189], v[66:69]
	v_mfma_f32_16x16x32_bf16 v[122:125], v[208:211], v[166:169], v[122:125]
	v_mfma_f32_16x16x32_bf16 v[114:117], v[216:219], v[166:169], v[114:117]
	v_mfma_f32_16x16x32_bf16 v[106:109], v[208:211], v[174:177], v[106:109]
	v_mfma_f32_16x16x32_bf16 v[98:101], v[216:219], v[174:177], v[98:101]
	v_mfma_f32_16x16x32_bf16 v[90:93], v[208:211], v[182:185], v[90:93]
	v_mfma_f32_16x16x32_bf16 v[82:85], v[216:219], v[182:185], v[82:85]
	v_mfma_f32_16x16x32_bf16 v[74:77], v[208:211], v[190:193], v[74:77]
	v_mfma_f32_16x16x32_bf16 v[66:69], v[216:219], v[190:193], v[66:69]
	s_mov_b32 m0, s57
	v_lshl_add_u64 v[140:141], v[222:223], 0, s[10:11]
	s_barrier
	ds_read_b128 v[162:165], v145 offset:49152
	ds_read_b128 v[166:169], v145 offset:50176
	ds_read_b128 v[170:173], v145 offset:51200
	ds_read_b128 v[174:177], v145 offset:52224
	ds_read_b128 v[178:181], v145 offset:53248
	ds_read_b128 v[182:185], v145 offset:54272
	ds_read_b128 v[186:189], v145 offset:55296
	ds_read_b128 v[190:193], v145 offset:56320
	global_load_lds_dwordx4 v[140:141], off
	v_lshl_add_u64 v[140:141], v[224:225], 0, s[10:11]
	s_mov_b32 m0, s58
	s_nop 0
	global_load_lds_dwordx4 v[140:141], off
	s_barrier
	s_waitcnt lgkmcnt(0)
	s_waitcnt lgkmcnt(0)
	v_mfma_f32_16x16x32_bf16 v[62:65], v[146:149], v[162:165], v[62:65]
	v_mfma_f32_16x16x32_bf16 v[54:57], v[154:157], v[162:165], v[54:57]
	v_mfma_f32_16x16x32_bf16 v[46:49], v[146:149], v[170:173], v[46:49]
	v_mfma_f32_16x16x32_bf16 v[38:41], v[154:157], v[170:173], v[38:41]
	v_mfma_f32_16x16x32_bf16 v[30:33], v[146:149], v[178:181], v[30:33]
	v_mfma_f32_16x16x32_bf16 v[22:25], v[154:157], v[178:181], v[22:25]
	v_mfma_f32_16x16x32_bf16 v[12:15], v[146:149], v[186:189], v[12:15]
	v_mfma_f32_16x16x32_bf16 v[4:7], v[154:157], v[186:189], v[4:7]
	v_mfma_f32_16x16x32_bf16 v[62:65], v[150:153], v[166:169], v[62:65]
	v_mfma_f32_16x16x32_bf16 v[54:57], v[158:161], v[166:169], v[54:57]
	v_mfma_f32_16x16x32_bf16 v[46:49], v[150:153], v[174:177], v[46:49]
	v_mfma_f32_16x16x32_bf16 v[38:41], v[158:161], v[174:177], v[38:41]
	v_mfma_f32_16x16x32_bf16 v[30:33], v[150:153], v[182:185], v[30:33]
	v_mfma_f32_16x16x32_bf16 v[22:25], v[158:161], v[182:185], v[22:25]
	v_mfma_f32_16x16x32_bf16 v[12:15], v[150:153], v[190:193], v[12:15]
	v_mfma_f32_16x16x32_bf16 v[4:7], v[158:161], v[190:193], v[4:7]
	s_barrier
	s_add_u32 s18, s18, 0x40080
	s_addc_u32 s19, s19, 0
	s_add_i32 s22, s22, s51
	v_lshl_add_u64 v[140:141], s[18:19], 0, v[16:17]
	s_mov_b32 m0, s22
	s_nop 0
	global_load_lds_dwordx4 v[140:141], off
	v_lshl_add_u64 v[140:141], s[18:19], 0, v[130:131]
	s_add_i32 m0, s22, 0x2000
	s_nop 0
	global_load_lds_dwordx4 v[140:141], off
	s_waitcnt vmcnt(10)
	s_barrier
	v_mfma_f32_16x16x32_bf16 v[58:61], v[194:197], v[162:165], v[58:61]
	v_mfma_f32_16x16x32_bf16 v[50:53], v[212:215], v[162:165], v[50:53]
	v_mfma_f32_16x16x32_bf16 v[42:45], v[194:197], v[170:173], v[42:45]
	v_mfma_f32_16x16x32_bf16 v[34:37], v[212:215], v[170:173], v[34:37]
	v_mfma_f32_16x16x32_bf16 v[26:29], v[194:197], v[178:181], v[26:29]
	v_mfma_f32_16x16x32_bf16 v[18:21], v[212:215], v[178:181], v[18:21]
	v_mfma_f32_16x16x32_bf16 v[8:11], v[194:197], v[186:189], v[8:11]
	v_mfma_f32_16x16x32_bf16 v[0:3], v[212:215], v[186:189], v[0:3]
	v_mfma_f32_16x16x32_bf16 v[58:61], v[208:211], v[166:169], v[58:61]
	v_mfma_f32_16x16x32_bf16 v[50:53], v[216:219], v[166:169], v[50:53]
	v_mfma_f32_16x16x32_bf16 v[42:45], v[208:211], v[174:177], v[42:45]
	v_mfma_f32_16x16x32_bf16 v[34:37], v[216:219], v[174:177], v[34:37]
	v_mfma_f32_16x16x32_bf16 v[26:29], v[208:211], v[182:185], v[26:29]
	v_mfma_f32_16x16x32_bf16 v[18:21], v[216:219], v[182:185], v[18:21]
	v_mfma_f32_16x16x32_bf16 v[8:11], v[208:211], v[190:193], v[8:11]
	v_mfma_f32_16x16x32_bf16 v[0:3], v[216:219], v[190:193], v[0:3]
	s_add_i32 s82, s82, 2
	s_add_u32 s61, s61, 0x100
	s_addc_u32 s79, s79, 0
	s_add_u32 s16, s16, 0x100
	s_addc_u32 s17, s17, 0
	s_cmp_gt_u32 s82, 13
	s_barrier
	s_cbranch_scc0 .LBB0_147
	v_mul_f32_e32 v208, 0xbfb8aa3b, v126
	v_mul_f32_e32 v209, 0xbfb8aa3b, v127
	v_mul_f32_e32 v210, 0xbfb8aa3b, v128
	v_mul_f32_e32 v211, 0xbfb8aa3b, v129
	v_mul_f32_e32 v212, 0xbfb8aa3b, v118
	v_mul_f32_e32 v213, 0xbfb8aa3b, v119
	v_mul_f32_e32 v214, 0xbfb8aa3b, v120
	v_mul_f32_e32 v215, 0xbfb8aa3b, v121
	v_exp_f32_e32 v208, v208
	v_exp_f32_e32 v209, v209
	v_exp_f32_e32 v210, v210
	v_exp_f32_e32 v211, v211
	v_exp_f32_e32 v212, v212
	v_exp_f32_e32 v213, v213
	v_exp_f32_e32 v214, v214
	v_exp_f32_e32 v215, v215
	v_add_f32_e32 v208, 1.0, v208
	v_add_f32_e32 v209, 1.0, v209
	v_add_f32_e32 v210, 1.0, v210
	v_add_f32_e32 v211, 1.0, v211
	v_add_f32_e32 v212, 1.0, v212
	v_add_f32_e32 v213, 1.0, v213
	v_add_f32_e32 v214, 1.0, v214
	v_add_f32_e32 v215, 1.0, v215
	v_rcp_f32_e32 v208, v208
	v_rcp_f32_e32 v209, v209
	v_rcp_f32_e32 v210, v210
	v_rcp_f32_e32 v211, v211
	v_rcp_f32_e32 v212, v212
	v_rcp_f32_e32 v213, v213
	v_rcp_f32_e32 v214, v214
	v_rcp_f32_e32 v215, v215
	v_mul_f32_e32 v216, v126, v208
	v_mul_f32_e32 v217, v127, v209
	v_mul_f32_e32 v218, v128, v210
	v_mul_f32_e32 v219, v129, v211
	v_mul_f32_e32 v220, v118, v212
	v_mul_f32_e32 v221, v119, v213
	v_mul_f32_e32 v222, v120, v214
	v_mul_f32_e32 v223, v121, v215
	v_mul_f32_e32 v216, v216, v122
	v_mul_f32_e32 v217, v217, v123
	v_mul_f32_e32 v218, v218, v124
	v_mul_f32_e32 v219, v219, v125
	v_mul_f32_e32 v220, v220, v114
	v_mul_f32_e32 v221, v221, v115
	v_mul_f32_e32 v222, v222, v116
	v_mul_f32_e32 v223, v223, v117
	v_lshl_or_b32 v148, s2, 7, v144
	v_lshl_add_u32 v146, s14, 8, v142
	v_ashrrev_i32_e32 v149, 31, v148
	v_mov_b64_e32 v[140:141], s[94:95]
	v_mad_i64_i32 v[150:151], s[16:17], v146, s65, v[140:141]
	v_lshlrev_b64 v[114:115], 1, v[148:149]
	v_lshl_add_u64 v[120:121], v[150:151], 0, v[114:115]
	v_cvt_pk_bf16_f32 v116, v216, v217
	v_cvt_pk_bf16_f32 v117, v218, v219
	v_cvt_pk_bf16_f32 v118, v220, v221
	v_cvt_pk_bf16_f32 v119, v222, v223
	global_store_dwordx4 v[120:121], v[116:119], off nt
	v_mul_f32_e32 v208, 0xbfb8aa3b, v110
	v_mul_f32_e32 v209, 0xbfb8aa3b, v111
	v_mul_f32_e32 v210, 0xbfb8aa3b, v112
	v_mul_f32_e32 v211, 0xbfb8aa3b, v113
	v_mul_f32_e32 v212, 0xbfb8aa3b, v102
	v_mul_f32_e32 v213, 0xbfb8aa3b, v103
	v_mul_f32_e32 v214, 0xbfb8aa3b, v104
	v_mul_f32_e32 v215, 0xbfb8aa3b, v105
	v_exp_f32_e32 v208, v208
	v_exp_f32_e32 v209, v209
	v_exp_f32_e32 v210, v210
	v_exp_f32_e32 v211, v211
	v_exp_f32_e32 v212, v212
	v_exp_f32_e32 v213, v213
	v_exp_f32_e32 v214, v214
	v_exp_f32_e32 v215, v215
	v_add_f32_e32 v208, 1.0, v208
	v_add_f32_e32 v209, 1.0, v209
	v_add_f32_e32 v210, 1.0, v210
	v_add_f32_e32 v211, 1.0, v211
	v_add_f32_e32 v212, 1.0, v212
	v_add_f32_e32 v213, 1.0, v213
	v_add_f32_e32 v214, 1.0, v214
	v_add_f32_e32 v215, 1.0, v215
	v_rcp_f32_e32 v208, v208
	v_rcp_f32_e32 v209, v209
	v_rcp_f32_e32 v210, v210
	v_rcp_f32_e32 v211, v211
	v_rcp_f32_e32 v212, v212
	v_rcp_f32_e32 v213, v213
	v_rcp_f32_e32 v214, v214
	v_rcp_f32_e32 v215, v215
	v_mul_f32_e32 v216, v110, v208
	v_mul_f32_e32 v217, v111, v209
	v_mul_f32_e32 v218, v112, v210
	v_mul_f32_e32 v219, v113, v211
	v_mul_f32_e32 v220, v102, v212
	v_mul_f32_e32 v221, v103, v213
	v_mul_f32_e32 v222, v104, v214
	v_mul_f32_e32 v223, v105, v215
	v_mul_f32_e32 v216, v216, v106
	v_mul_f32_e32 v217, v217, v107
	v_mul_f32_e32 v218, v218, v108
	v_mul_f32_e32 v219, v219, v109
	v_mul_f32_e32 v220, v220, v98
	v_mul_f32_e32 v221, v221, v99
	v_mul_f32_e32 v222, v222, v100
	v_mul_f32_e32 v223, v223, v101
	v_or_b32_e32 v116, 16, v146
	v_mad_i64_i32 v[116:117], s[16:17], v116, s65, v[140:141]
	v_lshl_add_u64 v[102:103], v[116:117], 0, v[114:115]
	v_cvt_pk_bf16_f32 v98, v216, v217
	v_cvt_pk_bf16_f32 v99, v218, v219
	v_cvt_pk_bf16_f32 v100, v220, v221
	v_cvt_pk_bf16_f32 v101, v222, v223
	global_store_dwordx4 v[102:103], v[98:101], off nt
	v_mul_f32_e32 v208, 0xbfb8aa3b, v94
	v_mul_f32_e32 v209, 0xbfb8aa3b, v95
	v_mul_f32_e32 v210, 0xbfb8aa3b, v96
	v_mul_f32_e32 v211, 0xbfb8aa3b, v97
	v_mul_f32_e32 v212, 0xbfb8aa3b, v86
	v_mul_f32_e32 v213, 0xbfb8aa3b, v87
	v_mul_f32_e32 v214, 0xbfb8aa3b, v88
	v_mul_f32_e32 v215, 0xbfb8aa3b, v89
	v_exp_f32_e32 v208, v208
	v_exp_f32_e32 v209, v209
	v_exp_f32_e32 v210, v210
	v_exp_f32_e32 v211, v211
	v_exp_f32_e32 v212, v212
	v_exp_f32_e32 v213, v213
	v_exp_f32_e32 v214, v214
	v_exp_f32_e32 v215, v215
	v_add_f32_e32 v208, 1.0, v208
	v_add_f32_e32 v209, 1.0, v209
	v_add_f32_e32 v210, 1.0, v210
	v_add_f32_e32 v211, 1.0, v211
	v_add_f32_e32 v212, 1.0, v212
	v_add_f32_e32 v213, 1.0, v213
	v_add_f32_e32 v214, 1.0, v214
	v_add_f32_e32 v215, 1.0, v215
	v_rcp_f32_e32 v208, v208
	v_rcp_f32_e32 v209, v209
	v_rcp_f32_e32 v210, v210
	v_rcp_f32_e32 v211, v211
	v_rcp_f32_e32 v212, v212
	v_rcp_f32_e32 v213, v213
	v_rcp_f32_e32 v214, v214
	v_rcp_f32_e32 v215, v215
	v_mul_f32_e32 v216, v94, v208
	v_mul_f32_e32 v217, v95, v209
	v_mul_f32_e32 v218, v96, v210
	v_mul_f32_e32 v219, v97, v211
	v_mul_f32_e32 v220, v86, v212
	v_mul_f32_e32 v221, v87, v213
	v_mul_f32_e32 v222, v88, v214
	v_mul_f32_e32 v223, v89, v215
	v_mul_f32_e32 v216, v216, v90
	v_mul_f32_e32 v217, v217, v91
	v_mul_f32_e32 v218, v218, v92
	v_mul_f32_e32 v219, v219, v93
	v_mul_f32_e32 v220, v220, v82
	v_mul_f32_e32 v221, v221, v83
	v_mul_f32_e32 v222, v222, v84
	v_mul_f32_e32 v223, v223, v85
	v_or_b32_e32 v98, 32, v146
	v_mad_i64_i32 v[98:99], s[16:17], v98, s65, v[140:141]
	v_lshl_add_u64 v[86:87], v[98:99], 0, v[114:115]
	v_cvt_pk_bf16_f32 v82, v216, v217
	v_cvt_pk_bf16_f32 v83, v218, v219
	v_cvt_pk_bf16_f32 v84, v220, v221
	v_cvt_pk_bf16_f32 v85, v222, v223
	global_store_dwordx4 v[86:87], v[82:85], off nt
	v_mul_f32_e32 v208, 0xbfb8aa3b, v78
	v_mul_f32_e32 v209, 0xbfb8aa3b, v79
	v_mul_f32_e32 v210, 0xbfb8aa3b, v80
	v_mul_f32_e32 v211, 0xbfb8aa3b, v81
	v_mul_f32_e32 v212, 0xbfb8aa3b, v70
	v_mul_f32_e32 v213, 0xbfb8aa3b, v71
	v_mul_f32_e32 v214, 0xbfb8aa3b, v72
	v_mul_f32_e32 v215, 0xbfb8aa3b, v73
	v_exp_f32_e32 v208, v208
	v_exp_f32_e32 v209, v209
	v_exp_f32_e32 v210, v210
	v_exp_f32_e32 v211, v211
	v_exp_f32_e32 v212, v212
	v_exp_f32_e32 v213, v213
	v_exp_f32_e32 v214, v214
	v_exp_f32_e32 v215, v215
	v_add_f32_e32 v208, 1.0, v208
	v_add_f32_e32 v209, 1.0, v209
	v_add_f32_e32 v210, 1.0, v210
	v_add_f32_e32 v211, 1.0, v211
	v_add_f32_e32 v212, 1.0, v212
	v_add_f32_e32 v213, 1.0, v213
	v_add_f32_e32 v214, 1.0, v214
	v_add_f32_e32 v215, 1.0, v215
	v_rcp_f32_e32 v208, v208
	v_rcp_f32_e32 v209, v209
	v_rcp_f32_e32 v210, v210
	v_rcp_f32_e32 v211, v211
	v_rcp_f32_e32 v212, v212
	v_rcp_f32_e32 v213, v213
	v_rcp_f32_e32 v214, v214
	v_rcp_f32_e32 v215, v215
	v_mul_f32_e32 v216, v78, v208
	v_mul_f32_e32 v217, v79, v209
	v_mul_f32_e32 v218, v80, v210
	v_mul_f32_e32 v219, v81, v211
	v_mul_f32_e32 v220, v70, v212
	v_mul_f32_e32 v221, v71, v213
	v_mul_f32_e32 v222, v72, v214
	v_mul_f32_e32 v223, v73, v215
	v_mul_f32_e32 v216, v216, v74
	v_mul_f32_e32 v217, v217, v75
	v_mul_f32_e32 v218, v218, v76
	v_mul_f32_e32 v219, v219, v77
	v_mul_f32_e32 v220, v220, v66
	v_mul_f32_e32 v221, v221, v67
	v_mul_f32_e32 v222, v222, v68
	v_mul_f32_e32 v223, v223, v69
	v_or_b32_e32 v82, 48, v146
	v_mad_i64_i32 v[82:83], s[16:17], v82, s65, v[140:141]
	v_lshl_add_u64 v[70:71], v[82:83], 0, v[114:115]
	v_cvt_pk_bf16_f32 v66, v216, v217
	v_cvt_pk_bf16_f32 v67, v218, v219
	v_cvt_pk_bf16_f32 v68, v220, v221
	v_cvt_pk_bf16_f32 v69, v222, v223
	global_store_dwordx4 v[70:71], v[66:69], off nt
	v_mul_f32_e32 v208, 0xbfb8aa3b, v62
	v_mul_f32_e32 v209, 0xbfb8aa3b, v63
	v_mul_f32_e32 v210, 0xbfb8aa3b, v64
	v_mul_f32_e32 v211, 0xbfb8aa3b, v65
	v_mul_f32_e32 v212, 0xbfb8aa3b, v54
	v_mul_f32_e32 v213, 0xbfb8aa3b, v55
	v_mul_f32_e32 v214, 0xbfb8aa3b, v56
	v_mul_f32_e32 v215, 0xbfb8aa3b, v57
	v_exp_f32_e32 v208, v208
	v_exp_f32_e32 v209, v209
	v_exp_f32_e32 v210, v210
	v_exp_f32_e32 v211, v211
	v_exp_f32_e32 v212, v212
	v_exp_f32_e32 v213, v213
	v_exp_f32_e32 v214, v214
	v_exp_f32_e32 v215, v215
	v_add_f32_e32 v208, 1.0, v208
	v_add_f32_e32 v209, 1.0, v209
	v_add_f32_e32 v210, 1.0, v210
	v_add_f32_e32 v211, 1.0, v211
	v_add_f32_e32 v212, 1.0, v212
	v_add_f32_e32 v213, 1.0, v213
	v_add_f32_e32 v214, 1.0, v214
	v_add_f32_e32 v215, 1.0, v215
	v_rcp_f32_e32 v208, v208
	v_rcp_f32_e32 v209, v209
	v_rcp_f32_e32 v210, v210
	v_rcp_f32_e32 v211, v211
	v_rcp_f32_e32 v212, v212
	v_rcp_f32_e32 v213, v213
	v_rcp_f32_e32 v214, v214
	v_rcp_f32_e32 v215, v215
	v_mul_f32_e32 v216, v62, v208
	v_mul_f32_e32 v217, v63, v209
	v_mul_f32_e32 v218, v64, v210
	v_mul_f32_e32 v219, v65, v211
	v_mul_f32_e32 v220, v54, v212
	v_mul_f32_e32 v221, v55, v213
	v_mul_f32_e32 v222, v56, v214
	v_mul_f32_e32 v223, v57, v215
	v_mul_f32_e32 v216, v216, v58
	v_mul_f32_e32 v217, v217, v59
	v_mul_f32_e32 v218, v218, v60
	v_mul_f32_e32 v219, v219, v61
	v_mul_f32_e32 v220, v220, v50
	v_mul_f32_e32 v221, v221, v51
	v_mul_f32_e32 v222, v222, v52
	v_mul_f32_e32 v223, v223, v53
	v_add_u32_e32 v66, 0x80, v146
	v_mad_i64_i32 v[66:67], s[16:17], v66, s65, v[140:141]
	v_lshl_add_u64 v[54:55], v[66:67], 0, v[114:115]
	v_cvt_pk_bf16_f32 v50, v216, v217
	v_cvt_pk_bf16_f32 v51, v218, v219
	v_cvt_pk_bf16_f32 v52, v220, v221
	v_cvt_pk_bf16_f32 v53, v222, v223
	global_store_dwordx4 v[54:55], v[50:53], off nt
	v_mul_f32_e32 v208, 0xbfb8aa3b, v46
	v_mul_f32_e32 v209, 0xbfb8aa3b, v47
	v_mul_f32_e32 v210, 0xbfb8aa3b, v48
	v_mul_f32_e32 v211, 0xbfb8aa3b, v49
	v_mul_f32_e32 v212, 0xbfb8aa3b, v38
	v_mul_f32_e32 v213, 0xbfb8aa3b, v39
	v_mul_f32_e32 v214, 0xbfb8aa3b, v40
	v_mul_f32_e32 v215, 0xbfb8aa3b, v41
	v_exp_f32_e32 v208, v208
	v_exp_f32_e32 v209, v209
	v_exp_f32_e32 v210, v210
	v_exp_f32_e32 v211, v211
	v_exp_f32_e32 v212, v212
	v_exp_f32_e32 v213, v213
	v_exp_f32_e32 v214, v214
	v_exp_f32_e32 v215, v215
	v_add_f32_e32 v208, 1.0, v208
	v_add_f32_e32 v209, 1.0, v209
	v_add_f32_e32 v210, 1.0, v210
	v_add_f32_e32 v211, 1.0, v211
	v_add_f32_e32 v212, 1.0, v212
	v_add_f32_e32 v213, 1.0, v213
	v_add_f32_e32 v214, 1.0, v214
	v_add_f32_e32 v215, 1.0, v215
	v_rcp_f32_e32 v208, v208
	v_rcp_f32_e32 v209, v209
	v_rcp_f32_e32 v210, v210
	v_rcp_f32_e32 v211, v211
	v_rcp_f32_e32 v212, v212
	v_rcp_f32_e32 v213, v213
	v_rcp_f32_e32 v214, v214
	v_rcp_f32_e32 v215, v215
	v_mul_f32_e32 v216, v46, v208
	v_mul_f32_e32 v217, v47, v209
	v_mul_f32_e32 v218, v48, v210
	v_mul_f32_e32 v219, v49, v211
	v_mul_f32_e32 v220, v38, v212
	v_mul_f32_e32 v221, v39, v213
	v_mul_f32_e32 v222, v40, v214
	v_mul_f32_e32 v223, v41, v215
	v_mul_f32_e32 v216, v216, v42
	v_mul_f32_e32 v217, v217, v43
	v_mul_f32_e32 v218, v218, v44
	v_mul_f32_e32 v219, v219, v45
	v_mul_f32_e32 v220, v220, v34
	v_mul_f32_e32 v221, v221, v35
	v_mul_f32_e32 v222, v222, v36
	v_mul_f32_e32 v223, v223, v37
	v_add_u32_e32 v50, 0x90, v146
	v_mad_i64_i32 v[50:51], s[16:17], v50, s65, v[140:141]
	v_lshl_add_u64 v[38:39], v[50:51], 0, v[114:115]
	v_cvt_pk_bf16_f32 v34, v216, v217
	v_cvt_pk_bf16_f32 v35, v218, v219
	v_cvt_pk_bf16_f32 v36, v220, v221
	v_cvt_pk_bf16_f32 v37, v222, v223
	global_store_dwordx4 v[38:39], v[34:37], off nt
	v_mul_f32_e32 v208, 0xbfb8aa3b, v30
	v_mul_f32_e32 v209, 0xbfb8aa3b, v31
	v_mul_f32_e32 v210, 0xbfb8aa3b, v32
	v_mul_f32_e32 v211, 0xbfb8aa3b, v33
	v_mul_f32_e32 v212, 0xbfb8aa3b, v22
	v_mul_f32_e32 v213, 0xbfb8aa3b, v23
	v_mul_f32_e32 v214, 0xbfb8aa3b, v24
	v_mul_f32_e32 v215, 0xbfb8aa3b, v25
	v_exp_f32_e32 v208, v208
	v_exp_f32_e32 v209, v209
	v_exp_f32_e32 v210, v210
	v_exp_f32_e32 v211, v211
	v_exp_f32_e32 v212, v212
	v_exp_f32_e32 v213, v213
	v_exp_f32_e32 v214, v214
	v_exp_f32_e32 v215, v215
	v_add_f32_e32 v208, 1.0, v208
	v_add_f32_e32 v209, 1.0, v209
	v_add_f32_e32 v210, 1.0, v210
	v_add_f32_e32 v211, 1.0, v211
	v_add_f32_e32 v212, 1.0, v212
	v_add_f32_e32 v213, 1.0, v213
	v_add_f32_e32 v214, 1.0, v214
	v_add_f32_e32 v215, 1.0, v215
	v_rcp_f32_e32 v208, v208
	v_rcp_f32_e32 v209, v209
	v_rcp_f32_e32 v210, v210
	v_rcp_f32_e32 v211, v211
	v_rcp_f32_e32 v212, v212
	v_rcp_f32_e32 v213, v213
	v_rcp_f32_e32 v214, v214
	v_rcp_f32_e32 v215, v215
	v_mul_f32_e32 v216, v30, v208
	v_mul_f32_e32 v217, v31, v209
	v_mul_f32_e32 v218, v32, v210
	v_mul_f32_e32 v219, v33, v211
	v_mul_f32_e32 v220, v22, v212
	v_mul_f32_e32 v221, v23, v213
	v_mul_f32_e32 v222, v24, v214
	v_mul_f32_e32 v223, v25, v215
	v_mul_f32_e32 v216, v216, v26
	v_mul_f32_e32 v217, v217, v27
	v_mul_f32_e32 v218, v218, v28
	v_mul_f32_e32 v219, v219, v29
	v_mul_f32_e32 v220, v220, v18
	v_mul_f32_e32 v221, v221, v19
	v_mul_f32_e32 v222, v222, v20
	v_mul_f32_e32 v223, v223, v21
	v_add_u32_e32 v34, 0xa0, v146
	v_mad_i64_i32 v[34:35], s[16:17], v34, s65, v[140:141]
	v_lshl_add_u64 v[22:23], v[34:35], 0, v[114:115]
	v_cvt_pk_bf16_f32 v18, v216, v217
	v_cvt_pk_bf16_f32 v19, v218, v219
	v_cvt_pk_bf16_f32 v20, v220, v221
	v_cvt_pk_bf16_f32 v21, v222, v223
	global_store_dwordx4 v[22:23], v[18:21], off nt
	v_mul_f32_e32 v208, 0xbfb8aa3b, v12
	v_mul_f32_e32 v209, 0xbfb8aa3b, v13
	v_mul_f32_e32 v210, 0xbfb8aa3b, v14
	v_mul_f32_e32 v211, 0xbfb8aa3b, v15
	v_mul_f32_e32 v212, 0xbfb8aa3b, v4
	v_mul_f32_e32 v213, 0xbfb8aa3b, v5
	v_mul_f32_e32 v214, 0xbfb8aa3b, v6
	v_mul_f32_e32 v215, 0xbfb8aa3b, v7
	v_exp_f32_e32 v208, v208
	v_exp_f32_e32 v209, v209
	v_exp_f32_e32 v210, v210
	v_exp_f32_e32 v211, v211
	v_exp_f32_e32 v212, v212
	v_exp_f32_e32 v213, v213
	v_exp_f32_e32 v214, v214
	v_exp_f32_e32 v215, v215
	v_add_f32_e32 v208, 1.0, v208
	v_add_f32_e32 v209, 1.0, v209
	v_add_f32_e32 v210, 1.0, v210
	v_add_f32_e32 v211, 1.0, v211
	v_add_f32_e32 v212, 1.0, v212
	v_add_f32_e32 v213, 1.0, v213
	v_add_f32_e32 v214, 1.0, v214
	v_add_f32_e32 v215, 1.0, v215
	v_rcp_f32_e32 v208, v208
	v_rcp_f32_e32 v209, v209
	v_rcp_f32_e32 v210, v210
	v_rcp_f32_e32 v211, v211
	v_rcp_f32_e32 v212, v212
	v_rcp_f32_e32 v213, v213
	v_rcp_f32_e32 v214, v214
	v_rcp_f32_e32 v215, v215
	v_mul_f32_e32 v216, v12, v208
	v_mul_f32_e32 v217, v13, v209
	v_mul_f32_e32 v218, v14, v210
	v_mul_f32_e32 v219, v15, v211
	v_mul_f32_e32 v220, v4, v212
	v_mul_f32_e32 v221, v5, v213
	v_mul_f32_e32 v222, v6, v214
	v_mul_f32_e32 v223, v7, v215
	v_mul_f32_e32 v216, v216, v8
	v_mul_f32_e32 v217, v217, v9
	v_mul_f32_e32 v218, v218, v10
	v_mul_f32_e32 v219, v219, v11
	v_mul_f32_e32 v220, v220, v0
	v_mul_f32_e32 v221, v221, v1
	v_mul_f32_e32 v222, v222, v2
	v_mul_f32_e32 v223, v223, v3
	v_add_u32_e32 v18, 0xb0, v146
	v_mad_i64_i32 v[18:19], s[16:17], v18, s65, v[140:141]
	v_lshl_add_u64 v[4:5], v[18:19], 0, v[114:115]
	v_cvt_pk_bf16_f32 v0, v216, v217
	v_cvt_pk_bf16_f32 v1, v218, v219
	v_cvt_pk_bf16_f32 v2, v220, v221
	v_cvt_pk_bf16_f32 v3, v222, v223
	global_store_dwordx4 v[4:5], v[0:3], off nt
	s_and_b64 vcc, exec, s[38:39]
	s_mov_b32 s2, s8
	s_mov_b32 s14, s28
	s_mov_b64 s[16:17], s[42:43]
	s_mov_b64 s[18:19], s[40:41]
	s_cbranch_vccz .LBB0_144
	s_waitcnt vmcnt(0)
	s_cmpk_gt_u32 s48, 0xff
	s_cbranch_scc1 .LBB0_151
	s_barrier

.LBB0_979:
	s_add_u32 s22, s20, 0xfffc0080
	s_addc_u32 s23, s21, -1
	s_add_i32 s61, 0, 0x10000
	v_add_u32_e32 v144, s61, v147
	ds_read_b128 v[140:143], v144
	ds_read_b128 v[150:153], v144 offset:1024
	ds_read_b128 v[154:157], v144 offset:2048
	ds_read_b128 v[158:161], v144 offset:3072
	s_cmp_eq_u32 s60, 12
	s_cselect_b32 s29, s9, s23
	s_cselect_b32 s28, s56, s22
	s_cselect_b32 s23, s5, s59
	s_cselect_b32 s22, s57, s58
	v_lshl_add_u64 v[144:145], s[20:21], 0, v[138:139]
	s_add_i32 m0, s12, 0xc000
	ds_read_b128 v[162:165], v149
	ds_read_b128 v[166:169], v149 offset:1024
	ds_read_b128 v[170:173], v149 offset:2048
	ds_read_b128 v[174:177], v149 offset:3072
	ds_read_b128 v[178:181], v149 offset:4096
	ds_read_b128 v[182:185], v149 offset:5120
	ds_read_b128 v[186:189], v149 offset:6144
	ds_read_b128 v[190:193], v149 offset:7168
	global_load_lds_dwordx4 v[144:145], off
	v_lshl_add_u64 v[144:145], s[20:21], 0, v[136:137]
	s_add_i32 m0, s12, 0xe000
	s_nop 0
	global_load_lds_dwordx4 v[144:145], off
	s_waitcnt lgkmcnt(8)
	s_waitcnt vmcnt(10)
	s_barrier
	s_waitcnt lgkmcnt(0)
	s_waitcnt lgkmcnt(0)
	v_mfma_f32_16x16x32_bf16 v[78:81], v[140:143], v[162:165], v[78:81]
	v_mfma_f32_16x16x32_bf16 v[74:77], v[154:157], v[162:165], v[74:77]
	v_mfma_f32_16x16x32_bf16 v[70:73], v[140:143], v[170:173], v[70:73]
	v_mfma_f32_16x16x32_bf16 v[66:69], v[154:157], v[170:173], v[66:69]
	v_mfma_f32_16x16x32_bf16 v[62:65], v[140:143], v[178:181], v[62:65]
	v_mfma_f32_16x16x32_bf16 v[54:57], v[154:157], v[178:181], v[54:57]
	v_mfma_f32_16x16x32_bf16 v[50:53], v[140:143], v[186:189], v[50:53]
	v_mfma_f32_16x16x32_bf16 v[42:45], v[154:157], v[186:189], v[42:45]
	v_mfma_f32_16x16x32_bf16 v[78:81], v[150:153], v[166:169], v[78:81]
	v_mfma_f32_16x16x32_bf16 v[74:77], v[158:161], v[166:169], v[74:77]
	v_mfma_f32_16x16x32_bf16 v[70:73], v[150:153], v[174:177], v[70:73]
	v_mfma_f32_16x16x32_bf16 v[66:69], v[158:161], v[174:177], v[66:69]
	v_mfma_f32_16x16x32_bf16 v[62:65], v[150:153], v[182:185], v[62:65]
	v_mfma_f32_16x16x32_bf16 v[54:57], v[158:161], v[182:185], v[54:57]
	v_mfma_f32_16x16x32_bf16 v[50:53], v[150:153], v[190:193], v[50:53]
	v_mfma_f32_16x16x32_bf16 v[42:45], v[158:161], v[190:193], v[42:45]
	s_barrier
	s_add_i32 s79, 0, 0x14000
	v_add_u32_e32 v144, s79, v147
	s_add_i32 s61, s61, s48
	ds_read_b128 v[194:197], v144
	ds_read_b128 v[208:211], v144 offset:1024
	ds_read_b128 v[212:215], v144 offset:2048
	ds_read_b128 v[216:219], v144 offset:3072
	v_lshl_add_u64 v[144:145], s[22:23], 0, v[16:17]
	s_mov_b32 m0, s61
	v_lshl_add_u64 v[220:221], s[22:23], 0, v[130:131]
	global_load_lds_dwordx4 v[144:145], off
	s_add_i32 m0, s61, 0x2000
	s_nop 0
	global_load_lds_dwordx4 v[220:221], off
	s_waitcnt vmcnt(10)
	s_barrier
	s_waitcnt lgkmcnt(0)
	s_waitcnt lgkmcnt(0)
	v_mfma_f32_16x16x32_bf16 v[126:129], v[194:197], v[162:165], v[126:129]
	v_mfma_f32_16x16x32_bf16 v[122:125], v[212:215], v[162:165], v[122:125]
	v_mfma_f32_16x16x32_bf16 v[118:121], v[194:197], v[170:173], v[118:121]
	v_mfma_f32_16x16x32_bf16 v[114:117], v[212:215], v[170:173], v[114:117]
	v_mfma_f32_16x16x32_bf16 v[110:113], v[194:197], v[178:181], v[110:113]
	v_mfma_f32_16x16x32_bf16 v[106:109], v[212:215], v[178:181], v[106:109]
	v_mfma_f32_16x16x32_bf16 v[102:105], v[194:197], v[186:189], v[102:105]
	v_mfma_f32_16x16x32_bf16 v[98:101], v[212:215], v[186:189], v[98:101]
	v_mfma_f32_16x16x32_bf16 v[126:129], v[208:211], v[166:169], v[126:129]
	v_mfma_f32_16x16x32_bf16 v[122:125], v[216:219], v[166:169], v[122:125]
	v_mfma_f32_16x16x32_bf16 v[118:121], v[208:211], v[174:177], v[118:121]
	v_mfma_f32_16x16x32_bf16 v[114:117], v[216:219], v[174:177], v[114:117]
	v_mfma_f32_16x16x32_bf16 v[110:113], v[208:211], v[182:185], v[110:113]
	v_mfma_f32_16x16x32_bf16 v[106:109], v[216:219], v[182:185], v[106:109]
	v_mfma_f32_16x16x32_bf16 v[102:105], v[208:211], v[190:193], v[102:105]
	v_mfma_f32_16x16x32_bf16 v[98:101], v[216:219], v[190:193], v[98:101]
	s_mov_b32 m0, s12
	v_lshl_add_u64 v[222:223], s[28:29], 0, v[134:135]
	s_barrier
	ds_read_b128 v[162:165], v149 offset:16384
	ds_read_b128 v[166:169], v149 offset:17408
	ds_read_b128 v[170:173], v149 offset:18432
	ds_read_b128 v[174:177], v149 offset:19456
	ds_read_b128 v[178:181], v149 offset:20480
	ds_read_b128 v[182:185], v149 offset:21504
	ds_read_b128 v[186:189], v149 offset:22528
	ds_read_b128 v[190:193], v149 offset:23552
	global_load_lds_dwordx4 v[222:223], off
	v_lshl_add_u64 v[224:225], s[28:29], 0, v[132:133]
	s_mov_b32 m0, s34
	s_nop 0
	global_load_lds_dwordx4 v[224:225], off
	s_barrier
	s_waitcnt lgkmcnt(0)
	s_waitcnt lgkmcnt(0)
	v_mfma_f32_16x16x32_bf16 v[34:37], v[140:143], v[162:165], v[34:37]
	v_mfma_f32_16x16x32_bf16 v[30:33], v[154:157], v[162:165], v[30:33]
	v_mfma_f32_16x16x32_bf16 v[22:25], v[140:143], v[170:173], v[22:25]
	v_mfma_f32_16x16x32_bf16 v[18:21], v[154:157], v[170:173], v[18:21]
	v_mfma_f32_16x16x32_bf16 v[12:15], v[140:143], v[178:181], v[12:15]
	v_mfma_f32_16x16x32_bf16 v[8:11], v[154:157], v[178:181], v[8:11]
	v_mfma_f32_16x16x32_bf16 v[4:7], v[140:143], v[186:189], v[4:7]
	v_mfma_f32_16x16x32_bf16 v[0:3], v[154:157], v[186:189], v[0:3]
	v_mfma_f32_16x16x32_bf16 v[34:37], v[150:153], v[166:169], v[34:37]
	v_mfma_f32_16x16x32_bf16 v[30:33], v[158:161], v[166:169], v[30:33]
	v_mfma_f32_16x16x32_bf16 v[22:25], v[150:153], v[174:177], v[22:25]
	v_mfma_f32_16x16x32_bf16 v[18:21], v[158:161], v[174:177], v[18:21]
	v_mfma_f32_16x16x32_bf16 v[12:15], v[150:153], v[182:185], v[12:15]
	v_mfma_f32_16x16x32_bf16 v[8:11], v[158:161], v[182:185], v[8:11]
	v_mfma_f32_16x16x32_bf16 v[4:7], v[150:153], v[190:193], v[4:7]
	v_mfma_f32_16x16x32_bf16 v[0:3], v[158:161], v[190:193], v[0:3]
	s_barrier
	s_add_u32 s82, s22, 0x40000
	s_addc_u32 s83, s23, 0
	s_add_i32 s61, s79, s48
	v_lshl_add_u64 v[140:141], s[82:83], 0, v[16:17]
	s_mov_b32 m0, s61
	s_nop 0
	global_load_lds_dwordx4 v[140:141], off
	v_lshl_add_u64 v[140:141], s[82:83], 0, v[130:131]
	s_add_i32 m0, s61, 0x2000
	s_nop 0
	global_load_lds_dwordx4 v[140:141], off
	s_waitcnt vmcnt(10)
	s_barrier
	v_mfma_f32_16x16x32_bf16 v[94:97], v[194:197], v[162:165], v[94:97]
	v_mfma_f32_16x16x32_bf16 v[90:93], v[212:215], v[162:165], v[90:93]
	v_mfma_f32_16x16x32_bf16 v[86:89], v[194:197], v[170:173], v[86:89]
	v_mfma_f32_16x16x32_bf16 v[82:85], v[212:215], v[170:173], v[82:85]
	v_mfma_f32_16x16x32_bf16 v[58:61], v[194:197], v[178:181], v[58:61]
	v_mfma_f32_16x16x32_bf16 v[46:49], v[212:215], v[178:181], v[46:49]
	v_mfma_f32_16x16x32_bf16 v[38:41], v[194:197], v[186:189], v[38:41]
	v_mfma_f32_16x16x32_bf16 v[26:29], v[212:215], v[186:189], v[26:29]
	v_mfma_f32_16x16x32_bf16 v[94:97], v[208:211], v[166:169], v[94:97]
	v_mfma_f32_16x16x32_bf16 v[90:93], v[216:219], v[166:169], v[90:93]
	v_mfma_f32_16x16x32_bf16 v[86:89], v[208:211], v[174:177], v[86:89]
	v_mfma_f32_16x16x32_bf16 v[82:85], v[216:219], v[174:177], v[82:85]
	v_mfma_f32_16x16x32_bf16 v[58:61], v[208:211], v[182:185], v[58:61]
	v_mfma_f32_16x16x32_bf16 v[46:49], v[216:219], v[182:185], v[46:49]
	v_mfma_f32_16x16x32_bf16 v[38:41], v[208:211], v[190:193], v[38:41]
	v_mfma_f32_16x16x32_bf16 v[26:29], v[216:219], v[190:193], v[26:29]
	s_add_i32 s61, 0, 0x18000
	v_add_u32_e32 v158, s61, v147
	s_barrier
	ds_read_b128 v[140:143], v158
	ds_read_b128 v[150:153], v158 offset:1024
	ds_read_b128 v[154:157], v158 offset:2048
	ds_read_b128 v[158:161], v158 offset:3072
	s_add_u32 s28, s28, 0x40000
	s_addc_u32 s29, s29, 0
	s_mov_b32 m0, s49
	v_lshl_add_u64 v[194:195], s[28:29], 0, v[134:135]
	ds_read_b128 v[162:165], v149 offset:32768
	ds_read_b128 v[166:169], v149 offset:33792
	ds_read_b128 v[170:173], v149 offset:34816
	ds_read_b128 v[174:177], v149 offset:35840
	ds_read_b128 v[178:181], v149 offset:36864
	ds_read_b128 v[182:185], v149 offset:37888
	ds_read_b128 v[186:189], v149 offset:38912
	ds_read_b128 v[190:193], v149 offset:39936
	global_load_lds_dwordx4 v[194:195], off
	v_lshl_add_u64 v[194:195], s[28:29], 0, v[132:133]
	s_mov_b32 m0, s50
	s_nop 0
	global_load_lds_dwordx4 v[194:195], off
	s_waitcnt lgkmcnt(8)
	s_waitcnt vmcnt(10)
	s_barrier
	s_waitcnt lgkmcnt(0)
	s_waitcnt lgkmcnt(0)
	v_mfma_f32_16x16x32_bf16 v[78:81], v[140:143], v[162:165], v[78:81]
	v_mfma_f32_16x16x32_bf16 v[74:77], v[154:157], v[162:165], v[74:77]
	v_mfma_f32_16x16x32_bf16 v[70:73], v[140:143], v[170:173], v[70:73]
	v_mfma_f32_16x16x32_bf16 v[66:69], v[154:157], v[170:173], v[66:69]
	v_mfma_f32_16x16x32_bf16 v[62:65], v[140:143], v[178:181], v[62:65]
	v_mfma_f32_16x16x32_bf16 v[54:57], v[154:157], v[178:181], v[54:57]
	v_mfma_f32_16x16x32_bf16 v[50:53], v[140:143], v[186:189], v[50:53]
	v_mfma_f32_16x16x32_bf16 v[42:45], v[154:157], v[186:189], v[42:45]
	v_mfma_f32_16x16x32_bf16 v[78:81], v[150:153], v[166:169], v[78:81]
	v_mfma_f32_16x16x32_bf16 v[74:77], v[158:161], v[166:169], v[74:77]
	v_mfma_f32_16x16x32_bf16 v[70:73], v[150:153], v[174:177], v[70:73]
	v_mfma_f32_16x16x32_bf16 v[66:69], v[158:161], v[174:177], v[66:69]
	v_mfma_f32_16x16x32_bf16 v[62:65], v[150:153], v[182:185], v[62:65]
	v_mfma_f32_16x16x32_bf16 v[54:57], v[158:161], v[182:185], v[54:57]
	v_mfma_f32_16x16x32_bf16 v[50:53], v[150:153], v[190:193], v[50:53]
	v_mfma_f32_16x16x32_bf16 v[42:45], v[158:161], v[190:193], v[42:45]
	s_barrier
	s_add_i32 s28, 0, 0x1c000
	s_add_i32 s29, s61, s48
	v_add_u32_e32 v216, s28, v147
	v_lshl_add_u64 v[144:145], v[144:145], 0, s[10:11]
	s_mov_b32 m0, s29
	ds_read_b128 v[194:197], v216
	ds_read_b128 v[208:211], v216 offset:1024
	ds_read_b128 v[212:215], v216 offset:2048
	ds_read_b128 v[216:219], v216 offset:3072
	global_load_lds_dwordx4 v[144:145], off
	v_lshl_add_u64 v[144:145], v[220:221], 0, s[10:11]
	s_add_i32 m0, s29, 0x2000
	s_nop 0
	global_load_lds_dwordx4 v[144:145], off
	s_waitcnt vmcnt(10)
	s_barrier
	s_waitcnt lgkmcnt(0)
	s_waitcnt lgkmcnt(0)
	v_mfma_f32_16x16x32_bf16 v[126:129], v[194:197], v[162:165], v[126:129]
	v_mfma_f32_16x16x32_bf16 v[122:125], v[212:215], v[162:165], v[122:125]
	v_mfma_f32_16x16x32_bf16 v[118:121], v[194:197], v[170:173], v[118:121]
	v_mfma_f32_16x16x32_bf16 v[114:117], v[212:215], v[170:173], v[114:117]
	v_mfma_f32_16x16x32_bf16 v[110:113], v[194:197], v[178:181], v[110:113]
	v_mfma_f32_16x16x32_bf16 v[106:109], v[212:215], v[178:181], v[106:109]
	v_mfma_f32_16x16x32_bf16 v[102:105], v[194:197], v[186:189], v[102:105]
	v_mfma_f32_16x16x32_bf16 v[98:101], v[212:215], v[186:189], v[98:101]
	v_mfma_f32_16x16x32_bf16 v[126:129], v[208:211], v[166:169], v[126:129]
	v_mfma_f32_16x16x32_bf16 v[122:125], v[216:219], v[166:169], v[122:125]
	v_mfma_f32_16x16x32_bf16 v[118:121], v[208:211], v[174:177], v[118:121]
	v_mfma_f32_16x16x32_bf16 v[114:117], v[216:219], v[174:177], v[114:117]
	v_mfma_f32_16x16x32_bf16 v[110:113], v[208:211], v[182:185], v[110:113]
	v_mfma_f32_16x16x32_bf16 v[106:109], v[216:219], v[182:185], v[106:109]
	v_mfma_f32_16x16x32_bf16 v[102:105], v[208:211], v[190:193], v[102:105]
	v_mfma_f32_16x16x32_bf16 v[98:101], v[216:219], v[190:193], v[98:101]
	s_mov_b32 m0, s51
	v_lshl_add_u64 v[144:145], v[222:223], 0, s[10:11]
	s_barrier
	ds_read_b128 v[162:165], v149 offset:49152
	ds_read_b128 v[166:169], v149 offset:50176
	ds_read_b128 v[170:173], v149 offset:51200
	ds_read_b128 v[174:177], v149 offset:52224
	ds_read_b128 v[178:181], v149 offset:53248
	ds_read_b128 v[182:185], v149 offset:54272
	ds_read_b128 v[186:189], v149 offset:55296
	ds_read_b128 v[190:193], v149 offset:56320
	global_load_lds_dwordx4 v[144:145], off
	v_lshl_add_u64 v[144:145], v[224:225], 0, s[10:11]
	s_mov_b32 m0, s52
	s_nop 0
	global_load_lds_dwordx4 v[144:145], off
	s_barrier
	s_waitcnt lgkmcnt(0)
	s_waitcnt lgkmcnt(0)
	v_mfma_f32_16x16x32_bf16 v[34:37], v[140:143], v[162:165], v[34:37]
	v_mfma_f32_16x16x32_bf16 v[30:33], v[154:157], v[162:165], v[30:33]
	v_mfma_f32_16x16x32_bf16 v[22:25], v[140:143], v[170:173], v[22:25]
	v_mfma_f32_16x16x32_bf16 v[18:21], v[154:157], v[170:173], v[18:21]
	v_mfma_f32_16x16x32_bf16 v[12:15], v[140:143], v[178:181], v[12:15]
	v_mfma_f32_16x16x32_bf16 v[8:11], v[154:157], v[178:181], v[8:11]
	v_mfma_f32_16x16x32_bf16 v[4:7], v[140:143], v[186:189], v[4:7]
	v_mfma_f32_16x16x32_bf16 v[0:3], v[154:157], v[186:189], v[0:3]
	v_mfma_f32_16x16x32_bf16 v[34:37], v[150:153], v[166:169], v[34:37]
	v_mfma_f32_16x16x32_bf16 v[30:33], v[158:161], v[166:169], v[30:33]
	v_mfma_f32_16x16x32_bf16 v[22:25], v[150:153], v[174:177], v[22:25]
	v_mfma_f32_16x16x32_bf16 v[18:21], v[158:161], v[174:177], v[18:21]
	v_mfma_f32_16x16x32_bf16 v[12:15], v[150:153], v[182:185], v[12:15]
	v_mfma_f32_16x16x32_bf16 v[8:11], v[158:161], v[182:185], v[8:11]
	v_mfma_f32_16x16x32_bf16 v[4:7], v[150:153], v[190:193], v[4:7]
	v_mfma_f32_16x16x32_bf16 v[0:3], v[158:161], v[190:193], v[0:3]
	s_barrier
	s_add_u32 s22, s22, 0x40080
	s_addc_u32 s23, s23, 0
	s_add_i32 s28, s28, s48
	v_lshl_add_u64 v[140:141], s[22:23], 0, v[16:17]
	s_mov_b32 m0, s28
	s_nop 0
	global_load_lds_dwordx4 v[140:141], off
	v_lshl_add_u64 v[140:141], s[22:23], 0, v[130:131]
	s_add_i32 m0, s28, 0x2000
	s_nop 0
	global_load_lds_dwordx4 v[140:141], off
	s_waitcnt vmcnt(10)
	s_barrier
	v_mfma_f32_16x16x32_bf16 v[94:97], v[194:197], v[162:165], v[94:97]
	v_mfma_f32_16x16x32_bf16 v[90:93], v[212:215], v[162:165], v[90:93]
	v_mfma_f32_16x16x32_bf16 v[86:89], v[194:197], v[170:173], v[86:89]
	v_mfma_f32_16x16x32_bf16 v[82:85], v[212:215], v[170:173], v[82:85]
	v_mfma_f32_16x16x32_bf16 v[58:61], v[194:197], v[178:181], v[58:61]
	v_mfma_f32_16x16x32_bf16 v[46:49], v[212:215], v[178:181], v[46:49]
	v_mfma_f32_16x16x32_bf16 v[38:41], v[194:197], v[186:189], v[38:41]
	v_mfma_f32_16x16x32_bf16 v[26:29], v[212:215], v[186:189], v[26:29]
	v_mfma_f32_16x16x32_bf16 v[94:97], v[208:211], v[166:169], v[94:97]
	v_mfma_f32_16x16x32_bf16 v[90:93], v[216:219], v[166:169], v[90:93]
	v_mfma_f32_16x16x32_bf16 v[86:89], v[208:211], v[174:177], v[86:89]
	v_mfma_f32_16x16x32_bf16 v[82:85], v[216:219], v[174:177], v[82:85]
	v_mfma_f32_16x16x32_bf16 v[58:61], v[208:211], v[182:185], v[58:61]
	v_mfma_f32_16x16x32_bf16 v[46:49], v[216:219], v[182:185], v[46:49]
	v_mfma_f32_16x16x32_bf16 v[38:41], v[208:211], v[190:193], v[38:41]
	v_mfma_f32_16x16x32_bf16 v[26:29], v[216:219], v[190:193], v[26:29]
	s_add_i32 s60, s60, 2
	s_add_u32 s58, s58, 0x100
	s_addc_u32 s59, s59, 0
	s_add_u32 s20, s20, 0x100
	s_addc_u32 s21, s21, 0
	s_cmp_gt_u32 s60, 13
	s_barrier
	s_cbranch_scc0 .LBB0_979
	v_lshl_or_b32 v144, s19, 8, v148
	v_lshl_add_u32 v140, s18, 8, v146
	v_ashrrev_i32_e32 v145, 31, v144
	v_mov_b64_e32 v[142:143], s[94:95]
	v_mad_i64_i32 v[150:151], s[20:21], v140, s66, v[142:143]
	v_lshlrev_b64 v[144:145], 1, v[144:145]
	v_lshl_add_u64 v[154:155], v[150:151], 0, v[144:145]
	v_cvt_pk_bf16_f32 v150, v78, v79
	v_cvt_pk_bf16_f32 v151, v80, v81
	v_cvt_pk_bf16_f32 v152, v74, v75
	v_cvt_pk_bf16_f32 v153, v76, v77
	global_store_dwordx4 v[154:155], v[150:153], off nt
	v_cvt_pk_bf16_f32 v126, v126, v127
	v_cvt_pk_bf16_f32 v127, v128, v129
	v_cvt_pk_bf16_f32 v128, v122, v123
	v_cvt_pk_bf16_f32 v129, v124, v125
	global_store_dwordx4 v[154:155], v[126:129], off offset:256 nt
	v_or_b32_e32 v122, 16, v140
	v_mad_i64_i32 v[124:125], s[20:21], v122, s66, v[142:143]
	v_lshl_add_u64 v[128:129], v[124:125], 0, v[144:145]
	v_cvt_pk_bf16_f32 v124, v70, v71
	v_cvt_pk_bf16_f32 v125, v72, v73
	v_cvt_pk_bf16_f32 v126, v66, v67
	v_cvt_pk_bf16_f32 v127, v68, v69
	global_store_dwordx4 v[128:129], v[124:127], off nt
	v_cvt_pk_bf16_f32 v118, v118, v119
	v_cvt_pk_bf16_f32 v119, v120, v121
	v_cvt_pk_bf16_f32 v120, v114, v115
	v_cvt_pk_bf16_f32 v121, v116, v117
	global_store_dwordx4 v[128:129], v[118:121], off offset:256 nt
	v_or_b32_e32 v114, 32, v140
	v_mad_i64_i32 v[116:117], s[20:21], v114, s66, v[142:143]
	v_lshl_add_u64 v[120:121], v[116:117], 0, v[144:145]
	v_cvt_pk_bf16_f32 v116, v62, v63
	v_cvt_pk_bf16_f32 v117, v64, v65
	v_cvt_pk_bf16_f32 v118, v54, v55
	v_cvt_pk_bf16_f32 v119, v56, v57
	global_store_dwordx4 v[120:121], v[116:119], off nt
	v_cvt_pk_bf16_f32 v110, v110, v111
	v_cvt_pk_bf16_f32 v111, v112, v113
	v_cvt_pk_bf16_f32 v112, v106, v107
	v_cvt_pk_bf16_f32 v113, v108, v109
	global_store_dwordx4 v[120:121], v[110:113], off offset:256 nt
	v_or_b32_e32 v106, 48, v140
	v_mad_i64_i32 v[108:109], s[20:21], v106, s66, v[142:143]
	v_lshl_add_u64 v[112:113], v[108:109], 0, v[144:145]
	v_cvt_pk_bf16_f32 v108, v50, v51
	v_cvt_pk_bf16_f32 v109, v52, v53
	v_cvt_pk_bf16_f32 v110, v42, v43
	v_cvt_pk_bf16_f32 v111, v44, v45
	global_store_dwordx4 v[112:113], v[108:111], off nt
	v_cvt_pk_bf16_f32 v102, v102, v103
	v_cvt_pk_bf16_f32 v103, v104, v105
	v_cvt_pk_bf16_f32 v104, v98, v99
	v_cvt_pk_bf16_f32 v105, v100, v101
	global_store_dwordx4 v[112:113], v[102:105], off offset:256 nt
	v_add_u32_e32 v98, 0x80, v140
	v_mad_i64_i32 v[100:101], s[20:21], v98, s66, v[142:143]
	v_lshl_add_u64 v[104:105], v[100:101], 0, v[144:145]
	v_cvt_pk_bf16_f32 v100, v34, v35
	v_cvt_pk_bf16_f32 v101, v36, v37
	v_cvt_pk_bf16_f32 v102, v30, v31
	v_cvt_pk_bf16_f32 v103, v32, v33
	global_store_dwordx4 v[104:105], v[100:103], off nt
	v_cvt_pk_bf16_f32 v94, v94, v95
	v_cvt_pk_bf16_f32 v95, v96, v97
	v_cvt_pk_bf16_f32 v96, v90, v91
	v_cvt_pk_bf16_f32 v97, v92, v93
	global_store_dwordx4 v[104:105], v[94:97], off offset:256 nt
	v_add_u32_e32 v90, 0x90, v140
	v_mad_i64_i32 v[92:93], s[20:21], v90, s66, v[142:143]
	v_lshl_add_u64 v[96:97], v[92:93], 0, v[144:145]
	v_cvt_pk_bf16_f32 v92, v22, v23
	v_cvt_pk_bf16_f32 v93, v24, v25
	v_cvt_pk_bf16_f32 v94, v18, v19
	v_cvt_pk_bf16_f32 v95, v20, v21
	global_store_dwordx4 v[96:97], v[92:95], off nt
	v_cvt_pk_bf16_f32 v86, v86, v87
	v_cvt_pk_bf16_f32 v87, v88, v89
	v_cvt_pk_bf16_f32 v88, v82, v83
	v_cvt_pk_bf16_f32 v89, v84, v85
	global_store_dwordx4 v[96:97], v[86:89], off offset:256 nt
	v_add_u32_e32 v82, 0xa0, v140
	v_mad_i64_i32 v[84:85], s[20:21], v82, s66, v[142:143]
	v_lshl_add_u64 v[88:89], v[84:85], 0, v[144:145]
	v_cvt_pk_bf16_f32 v84, v12, v13
	v_cvt_pk_bf16_f32 v85, v14, v15
	v_cvt_pk_bf16_f32 v86, v8, v9
	v_cvt_pk_bf16_f32 v87, v10, v11
	global_store_dwordx4 v[88:89], v[84:87], off nt
	v_cvt_pk_bf16_f32 v58, v58, v59
	v_cvt_pk_bf16_f32 v59, v60, v61
	v_cvt_pk_bf16_f32 v60, v46, v47
	v_cvt_pk_bf16_f32 v61, v48, v49
	global_store_dwordx4 v[88:89], v[58:61], off offset:256 nt
	v_add_u32_e32 v46, 0xb0, v140
	v_mad_i64_i32 v[48:49], s[20:21], v46, s66, v[142:143]
	v_lshl_add_u64 v[48:49], v[48:49], 0, v[144:145]
	v_cvt_pk_bf16_f32 v58, v4, v5
	v_cvt_pk_bf16_f32 v59, v6, v7
	v_cvt_pk_bf16_f32 v60, v0, v1
	v_cvt_pk_bf16_f32 v61, v2, v3
	global_store_dwordx4 v[48:49], v[58:61], off nt
	v_cvt_pk_bf16_f32 v38, v38, v39
	v_cvt_pk_bf16_f32 v39, v40, v41
	v_cvt_pk_bf16_f32 v40, v26, v27
	v_cvt_pk_bf16_f32 v41, v28, v29
	global_store_dwordx4 v[48:49], v[38:41], off offset:256 nt
	s_cmp_eq_u32 s19, 34
	s_cselect_b64 s[18:19], -1, 0
	s_and_b64 s[20:21], s[38:39], s[18:19]
	s_and_saveexec_b64 s[18:19], s[20:21]
	s_cbranch_execz .LBB0_975
	v_ashrrev_i32_e32 v141, 31, v140
	v_lshlrev_b64 v[26:27], 5, v[140:141]
	v_ashrrev_i32_e32 v123, 31, v122
	v_lshl_add_u64 v[26:27], s[42:43], 0, v[26:27]
	global_store_dwordx4 v[26:27], v[78:81], off nt
	global_store_dwordx4 v[26:27], v[74:77], off offset:16 nt
	v_lshlrev_b64 v[26:27], 5, v[122:123]
	v_ashrrev_i32_e32 v115, 31, v114
	v_lshl_add_u64 v[26:27], s[42:43], 0, v[26:27]
	global_store_dwordx4 v[26:27], v[70:73], off nt
	global_store_dwordx4 v[26:27], v[66:69], off offset:16 nt
	v_lshlrev_b64 v[26:27], 5, v[114:115]
	v_ashrrev_i32_e32 v107, 31, v106
	v_lshl_add_u64 v[26:27], s[42:43], 0, v[26:27]
	global_store_dwordx4 v[26:27], v[62:65], off nt
	global_store_dwordx4 v[26:27], v[54:57], off offset:16 nt
	v_lshlrev_b64 v[26:27], 5, v[106:107]
	v_ashrrev_i32_e32 v99, 31, v98
	v_lshl_add_u64 v[26:27], s[42:43], 0, v[26:27]
	global_store_dwordx4 v[26:27], v[50:53], off nt
	global_store_dwordx4 v[26:27], v[42:45], off offset:16 nt
	v_lshlrev_b64 v[26:27], 5, v[98:99]
	v_ashrrev_i32_e32 v91, 31, v90
	v_lshl_add_u64 v[26:27], s[42:43], 0, v[26:27]
	global_store_dwordx4 v[26:27], v[34:37], off nt
	global_store_dwordx4 v[26:27], v[30:33], off offset:16 nt
	v_lshlrev_b64 v[26:27], 5, v[90:91]
	v_ashrrev_i32_e32 v83, 31, v82
	v_lshl_add_u64 v[26:27], s[42:43], 0, v[26:27]
	global_store_dwordx4 v[26:27], v[22:25], off nt
	global_store_dwordx4 v[26:27], v[18:21], off offset:16 nt
	v_ashrrev_i32_e32 v47, 31, v46
	s_nop 0
	v_lshlrev_b64 v[18:19], 5, v[82:83]
	v_lshl_add_u64 v[18:19], s[42:43], 0, v[18:19]
	global_store_dwordx4 v[18:19], v[12:15], off nt
	global_store_dwordx4 v[18:19], v[8:11], off offset:16 nt
	s_nop 1
	v_lshlrev_b64 v[8:9], 5, v[46:47]
	v_lshl_add_u64 v[8:9], s[42:43], 0, v[8:9]
	global_store_dwordx4 v[8:9], v[4:7], off nt
	global_store_dwordx4 v[8:9], v[0:3], off offset:16 nt
	s_branch .LBB0_975
